# attention ring loops: the skip-rescale branch tests m_old != m_new directly instead of waiting for exp2(m_old-m_new) != 1.0 (bit-identical result)
# speedup vs baseline: 1.0039x; 1.0002x over previous
.LBB0_1158:
	v_max_f32_e32 v108, v35, v35
	v_max_f32_e32 v110, v34, v34
	v_max_f32_e32 v108, v110, v108
	v_max3_f32 v108, v108, v36, v37
	v_max3_f32 v108, v108, v38, v39
	v_max3_f32 v108, v108, v40, v41
	v_max3_f32 v108, v108, v42, v43
	v_max3_f32 v108, v108, v44, v45
	v_max3_f32 v108, v108, v46, v47
	v_max3_f32 v108, v108, v48, v49
	v_max3_f32 v108, v108, v50, v51
	v_max3_f32 v108, v108, v52, v53
	v_max3_f32 v108, v108, v54, v55
	v_max3_f32 v108, v108, v56, v57
	v_max3_f32 v108, v108, v58, v59
	v_max3_f32 v108, v108, v60, v61
	v_max3_f32 v108, v108, v62, v63
	v_max3_f32 v108, v108, v64, v65
	ds_bpermute_b32 v110, v209, v108
	v_sub_co_u32_e64 v111, vcc, s42, 32
	v_lshrrev_b32_e32 v0, s42, v102
	v_lshrrev_b32_e32 v111, v111, v103
	v_cndmask_b32_e32 v0, v111, v0, vcc
	v_and_b32_e32 v0, 1, v0
	s_waitcnt lgkmcnt(0)
	v_max_f32_e32 v110, v110, v110
	v_max_f32_e32 v108, v108, v110
	v_cmp_eq_u32_e64 s[2:3], 0, v0
	s_nop 1
	v_cndmask_b32_e64 v0, v108, v196, s[2:3]
	v_max_f32_e32 v108, v116, v116
	v_max_f32_e32 v117, v108, v0
	v_cmp_neq_f32_e32 vcc, v116, v117
	v_sub_f32_e32 v0, v116, v117
	v_exp_f32_e32 v108, v0
	s_cbranch_vccz .LBB0_1160
	v_pk_mul_f32 v[32:33], v[32:33], v[108:109] op_sel_hi:[1,0]
	v_pk_mul_f32 v[30:31], v[30:31], v[108:109] op_sel_hi:[1,0]
	v_pk_mul_f32 v[28:29], v[28:29], v[108:109] op_sel_hi:[1,0]
	v_pk_mul_f32 v[26:27], v[26:27], v[108:109] op_sel_hi:[1,0]
	v_pk_mul_f32 v[24:25], v[24:25], v[108:109] op_sel_hi:[1,0]
	v_pk_mul_f32 v[22:23], v[22:23], v[108:109] op_sel_hi:[1,0]
	v_pk_mul_f32 v[20:21], v[20:21], v[108:109] op_sel_hi:[1,0]
	v_pk_mul_f32 v[18:19], v[18:19], v[108:109] op_sel_hi:[1,0]
	v_pk_mul_f32 v[16:17], v[16:17], v[108:109] op_sel_hi:[1,0]
	v_pk_mul_f32 v[14:15], v[14:15], v[108:109] op_sel_hi:[1,0]
	v_pk_mul_f32 v[12:13], v[12:13], v[108:109] op_sel_hi:[1,0]
	v_pk_mul_f32 v[10:11], v[10:11], v[108:109] op_sel_hi:[1,0]
	v_pk_mul_f32 v[8:9], v[8:9], v[108:109] op_sel_hi:[1,0]
	v_pk_mul_f32 v[6:7], v[6:7], v[108:109] op_sel_hi:[1,0]
	v_pk_mul_f32 v[4:5], v[4:5], v[108:109] op_sel_hi:[1,0]
	v_pk_mul_f32 v[2:3], v[2:3], v[108:109] op_sel_hi:[1,0]

.LBB0_1171:
	v_max_f32_e32 v108, v67, v67
	v_max_f32_e32 v110, v66, v66
	v_max_f32_e32 v108, v110, v108
	v_max3_f32 v108, v108, v68, v69
	v_max3_f32 v108, v108, v70, v71
	v_max3_f32 v108, v108, v72, v73
	v_max3_f32 v108, v108, v74, v75
	v_max3_f32 v108, v108, v76, v77
	v_max3_f32 v108, v108, v78, v79
	v_max3_f32 v108, v108, v80, v81
	v_max3_f32 v108, v108, v82, v83
	v_max3_f32 v108, v108, v84, v85
	v_max3_f32 v108, v108, v86, v87
	v_max3_f32 v108, v108, v88, v89
	v_max3_f32 v108, v108, v90, v91
	v_max3_f32 v108, v108, v92, v93
	v_max3_f32 v108, v108, v94, v95
	v_max3_f32 v108, v108, v96, v97
	ds_bpermute_b32 v110, v209, v108
	s_cmp_lt_u32 s42, 32
	s_cselect_b64 vcc, -1, 0
	s_sub_i32 s2, s42, 31
	v_lshrrev_b32_e32 v0, s40, v102
	v_lshrrev_b32_e32 v111, s2, v103
	v_cndmask_b32_e32 v0, v111, v0, vcc
	v_and_b32_e32 v0, 1, v0
	s_waitcnt lgkmcnt(0)
	v_max_f32_e32 v110, v110, v110
	v_max_f32_e32 v108, v108, v110
	v_cmp_eq_u32_e64 s[2:3], 0, v0
	s_nop 1
	v_cndmask_b32_e64 v0, v108, v196, s[2:3]
	v_max_f32_e32 v108, v117, v117
	v_max_f32_e32 v116, v108, v0
	v_cmp_neq_f32_e32 vcc, v117, v116
	v_sub_f32_e32 v0, v117, v116
	v_exp_f32_e32 v108, v0
	s_cbranch_vccz .LBB0_1173
	v_pk_mul_f32 v[32:33], v[32:33], v[108:109] op_sel_hi:[1,0]
	v_pk_mul_f32 v[30:31], v[30:31], v[108:109] op_sel_hi:[1,0]
	v_pk_mul_f32 v[28:29], v[28:29], v[108:109] op_sel_hi:[1,0]
	v_pk_mul_f32 v[26:27], v[26:27], v[108:109] op_sel_hi:[1,0]
	v_pk_mul_f32 v[24:25], v[24:25], v[108:109] op_sel_hi:[1,0]
	v_pk_mul_f32 v[22:23], v[22:23], v[108:109] op_sel_hi:[1,0]
	v_pk_mul_f32 v[20:21], v[20:21], v[108:109] op_sel_hi:[1,0]
	v_pk_mul_f32 v[18:19], v[18:19], v[108:109] op_sel_hi:[1,0]
	v_pk_mul_f32 v[16:17], v[16:17], v[108:109] op_sel_hi:[1,0]
	v_pk_mul_f32 v[14:15], v[14:15], v[108:109] op_sel_hi:[1,0]
	v_pk_mul_f32 v[12:13], v[12:13], v[108:109] op_sel_hi:[1,0]
	v_pk_mul_f32 v[10:11], v[10:11], v[108:109] op_sel_hi:[1,0]
	v_pk_mul_f32 v[8:9], v[8:9], v[108:109] op_sel_hi:[1,0]
	v_pk_mul_f32 v[6:7], v[6:7], v[108:109] op_sel_hi:[1,0]
	v_pk_mul_f32 v[4:5], v[4:5], v[108:109] op_sel_hi:[1,0]
	v_pk_mul_f32 v[2:3], v[2:3], v[108:109] op_sel_hi:[1,0]

.LBB0_1188:
	v_max_f32_e32 v0, v35, v35
	v_max_f32_e32 v102, v34, v34
	v_max_f32_e32 v0, v102, v0
	v_max3_f32 v0, v0, v36, v37
	v_max3_f32 v0, v0, v38, v39
	v_max3_f32 v0, v0, v40, v41
	v_max3_f32 v0, v0, v42, v43
	v_max3_f32 v0, v0, v44, v45
	v_max3_f32 v0, v0, v46, v47
	v_max3_f32 v0, v0, v48, v49
	v_max3_f32 v0, v0, v50, v51
	v_max3_f32 v0, v0, v52, v53
	v_max3_f32 v0, v0, v54, v55
	v_max3_f32 v0, v0, v56, v57
	v_max3_f32 v0, v0, v58, v59
	v_max3_f32 v0, v0, v60, v61
	v_max3_f32 v0, v0, v62, v63
	v_max3_f32 v0, v0, v64, v65
	ds_bpermute_b32 v102, v209, v0
	s_waitcnt lgkmcnt(0)
	v_max3_f32 v108, v107, v0, v102
	v_cmp_neq_f32_e32 vcc, v107, v108
	v_sub_f32_e32 v0, v107, v108
	v_exp_f32_e32 v102, v0
	s_cbranch_vccz .LBB0_1190
	v_pk_mul_f32 v[16:17], v[16:17], v[102:103] op_sel_hi:[1,0]
	v_pk_mul_f32 v[14:15], v[14:15], v[102:103] op_sel_hi:[1,0]
	v_pk_mul_f32 v[12:13], v[12:13], v[102:103] op_sel_hi:[1,0]
	v_pk_mul_f32 v[10:11], v[10:11], v[102:103] op_sel_hi:[1,0]
	v_pk_mul_f32 v[8:9], v[8:9], v[102:103] op_sel_hi:[1,0]
	v_pk_mul_f32 v[6:7], v[6:7], v[102:103] op_sel_hi:[1,0]
	v_pk_mul_f32 v[4:5], v[4:5], v[102:103] op_sel_hi:[1,0]
	v_pk_mul_f32 v[2:3], v[2:3], v[102:103] op_sel_hi:[1,0]
	v_pk_mul_f32 v[32:33], v[32:33], v[102:103] op_sel_hi:[1,0]
	v_pk_mul_f32 v[30:31], v[30:31], v[102:103] op_sel_hi:[1,0]
	v_pk_mul_f32 v[28:29], v[28:29], v[102:103] op_sel_hi:[1,0]
	v_pk_mul_f32 v[26:27], v[26:27], v[102:103] op_sel_hi:[1,0]
	v_pk_mul_f32 v[24:25], v[24:25], v[102:103] op_sel_hi:[1,0]
	v_pk_mul_f32 v[22:23], v[22:23], v[102:103] op_sel_hi:[1,0]
	v_pk_mul_f32 v[20:21], v[20:21], v[102:103] op_sel_hi:[1,0]
	v_pk_mul_f32 v[18:19], v[18:19], v[102:103] op_sel_hi:[1,0]

.LBB0_1199:
	v_max_f32_e32 v0, v67, v67
	v_max_f32_e32 v102, v66, v66
	v_max_f32_e32 v0, v102, v0
	v_max3_f32 v0, v0, v68, v69
	v_max3_f32 v0, v0, v70, v71
	v_max3_f32 v0, v0, v72, v73
	v_max3_f32 v0, v0, v74, v75
	v_max3_f32 v0, v0, v76, v77
	v_max3_f32 v0, v0, v78, v79
	v_max3_f32 v0, v0, v80, v81
	v_max3_f32 v0, v0, v82, v83
	v_max3_f32 v0, v0, v84, v85
	v_max3_f32 v0, v0, v86, v87
	v_max3_f32 v0, v0, v88, v89
	v_max3_f32 v0, v0, v90, v91
	v_max3_f32 v0, v0, v92, v93
	v_max3_f32 v0, v0, v94, v95
	v_max3_f32 v0, v0, v96, v97
	ds_bpermute_b32 v102, v209, v0
	s_waitcnt lgkmcnt(0)
	v_max3_f32 v107, v108, v0, v102
	v_cmp_neq_f32_e32 vcc, v108, v107
	v_sub_f32_e32 v0, v108, v107
	v_exp_f32_e32 v102, v0
	s_cbranch_vccz .LBB0_1201
	v_pk_mul_f32 v[16:17], v[16:17], v[102:103] op_sel_hi:[1,0]
	v_pk_mul_f32 v[14:15], v[14:15], v[102:103] op_sel_hi:[1,0]
	v_pk_mul_f32 v[12:13], v[12:13], v[102:103] op_sel_hi:[1,0]
	v_pk_mul_f32 v[10:11], v[10:11], v[102:103] op_sel_hi:[1,0]
	v_pk_mul_f32 v[8:9], v[8:9], v[102:103] op_sel_hi:[1,0]
	v_pk_mul_f32 v[6:7], v[6:7], v[102:103] op_sel_hi:[1,0]
	v_pk_mul_f32 v[4:5], v[4:5], v[102:103] op_sel_hi:[1,0]
	v_pk_mul_f32 v[2:3], v[2:3], v[102:103] op_sel_hi:[1,0]
	v_pk_mul_f32 v[32:33], v[32:33], v[102:103] op_sel_hi:[1,0]
	v_pk_mul_f32 v[30:31], v[30:31], v[102:103] op_sel_hi:[1,0]
	v_pk_mul_f32 v[28:29], v[28:29], v[102:103] op_sel_hi:[1,0]
	v_pk_mul_f32 v[26:27], v[26:27], v[102:103] op_sel_hi:[1,0]
	v_pk_mul_f32 v[24:25], v[24:25], v[102:103] op_sel_hi:[1,0]
	v_pk_mul_f32 v[22:23], v[22:23], v[102:103] op_sel_hi:[1,0]
	v_pk_mul_f32 v[20:21], v[20:21], v[102:103] op_sel_hi:[1,0]
	v_pk_mul_f32 v[18:19], v[18:19], v[102:103] op_sel_hi:[1,0]
